# P4 reorder for workgroups 128..255 (diff unit 1, dilated pass 1, diff unit 2) so the dilated pass of one half overlaps the differential units of the other
# speedup vs baseline: 1.0148x; 1.0029x over previous
.LBB0_579:
	s_waitcnt lgkmcnt(0)
	v_mov_b32_e32 v0, 0
	s_barrier
	s_load_dwordx16 s[36:51], s[0:1], 0x30
	v_mbcnt_lo_u32_b32 v0, -1, v0
	v_mbcnt_hi_u32_b32 v0, -1, v0
	v_ashrrev_i32_e32 v1, 31, v0
	v_lshlrev_b64 v[2:3], 2, v[0:1]
	s_waitcnt lgkmcnt(0)
	v_lshl_add_u64 v[4:5], s[36:37], 0, v[2:3]
	global_load_dword v1, v[4:5], off
	global_load_dword v6, v[4:5], off offset:256
	v_lshl_add_u64 v[4:5], s[38:39], 0, v[2:3]
	global_load_dword v7, v[4:5], off
	global_load_dword v8, v[4:5], off offset:256
	v_lshl_add_u64 v[4:5], s[40:41], 0, v[2:3]
	global_load_dword v9, v[4:5], off
	v_lshl_add_u64 v[4:5], s[42:43], 0, v[2:3]
	global_load_dword v10, v[4:5], off
	v_lshl_add_u64 v[4:5], s[44:45], 0, v[2:3]
	global_load_dword v11, v[4:5], off
	v_lshl_add_u64 v[4:5], s[46:47], 0, v[2:3]
	global_load_dword v12, v[4:5], off
	v_lshl_add_u64 v[4:5], s[48:49], 0, v[2:3]
	v_lshl_add_u64 v[2:3], s[50:51], 0, v[2:3]
	global_load_dword v4, v[4:5], off
	v_lshlrev_b32_e32 v0, 2, v0
	global_load_dword v2, v[2:3], off
	v_xor_b32_e32 v5, 4, v0
	v_xor_b32_e32 v13, 8, v0
	v_xor_b32_e32 v14, 16, v0
	v_xor_b32_e32 v15, 32, v0
	v_xor_b32_e32 v16, 64, v0
	v_xor_b32_e32 v17, 0x80, v0
	v_mov_b32_e32 v3, 0x3fb8aa3b
	s_add_u32 s16, s26, 0x15400000
	s_addc_u32 s17, s27, 0
	s_add_u32 s18, s26, 0x17400000
	s_addc_u32 s19, s27, 0
	s_cmpk_lt_i32 s60, 0x800
	v_mov_b32_e32 v209, 0
	s_cselect_b64 s[20:21], -1, 0
	s_cmpk_gt_i32 s60, 0x7ff
	s_mul_i32 s63, s90, 0x4a00
	s_waitcnt vmcnt(9)
	v_max_f32_e64 v1, |v1|, |v1|
	s_waitcnt vmcnt(8)
	v_max_f32_e64 v0, |v6|, |v6|
	s_waitcnt vmcnt(7)
	v_max_f32_e64 v7, |v7|, |v7|
	s_waitcnt vmcnt(6)
	v_max_f32_e64 v6, |v8|, |v8|
	v_max_f32_e32 v0, v1, v0
	s_waitcnt vmcnt(5)
	v_and_b32_e32 v8, 0x7fffffff, v9
	v_max_f32_e32 v1, v7, v6
	s_waitcnt vmcnt(4)
	v_and_b32_e32 v18, 0x7fffffff, v10
	ds_bpermute_b32 v6, v5, v8
	ds_bpermute_b32 v7, v5, v18
	v_max_f32_e64 v9, |v9|, |v9|
	s_waitcnt vmcnt(2)
	v_mul_f32_e32 v19, v11, v12
	ds_bpermute_b32 v8, v5, v19
	ds_bpermute_b32 v19, v5, v0
	v_max_f32_e64 v10, |v10|, |v10|
	s_waitcnt lgkmcnt(3)
	v_max_f32_e32 v6, v6, v6
	s_waitcnt vmcnt(0)
	v_mul_f32_e32 v20, v4, v2
	ds_bpermute_b32 v18, v5, v20
	ds_bpermute_b32 v5, v5, v1
	s_waitcnt lgkmcnt(4)
	v_max_f32_e32 v7, v7, v7
	s_waitcnt lgkmcnt(3)
	v_fmac_f32_e32 v8, v11, v12
	s_waitcnt lgkmcnt(1)
	v_fmac_f32_e32 v18, v4, v2
	v_max_f32_e32 v2, v19, v19
	s_waitcnt lgkmcnt(0)
	v_max_f32_e32 v4, v5, v5
	v_max_f32_e32 v0, v0, v2
	v_max_f32_e32 v5, v9, v6
	v_max_f32_e32 v6, v10, v7
	v_max_f32_e32 v1, v1, v4
	ds_bpermute_b32 v10, v13, v0
	ds_bpermute_b32 v7, v13, v8
	ds_bpermute_b32 v11, v13, v1
	ds_bpermute_b32 v9, v13, v18
	ds_bpermute_b32 v2, v13, v5
	s_waitcnt lgkmcnt(4)
	v_max_f32_e32 v10, v10, v10
	s_waitcnt lgkmcnt(3)
	v_add_f32_e32 v7, v8, v7
	s_waitcnt lgkmcnt(2)
	v_max_f32_e32 v11, v11, v11
	v_max_f32_e32 v0, v0, v10
	s_waitcnt lgkmcnt(1)
	v_add_f32_e32 v8, v18, v9
	ds_bpermute_b32 v9, v14, v7
	v_max_f32_e32 v1, v1, v11
	ds_bpermute_b32 v10, v14, v0
	s_waitcnt lgkmcnt(2)
	v_max_f32_e32 v2, v2, v2
	ds_bpermute_b32 v11, v14, v1
	v_max_f32_e32 v2, v5, v2
	ds_bpermute_b32 v5, v14, v2
	ds_bpermute_b32 v4, v13, v6
	s_waitcnt lgkmcnt(4)
	v_add_f32_e32 v7, v7, v9
	s_waitcnt lgkmcnt(3)
	v_max_f32_e32 v9, v10, v10
	s_waitcnt lgkmcnt(2)
	v_max_f32_e32 v10, v11, v11
	v_max_f32_e32 v0, v0, v9
	v_max_f32_e32 v1, v1, v10
	ds_bpermute_b32 v9, v15, v0
	s_waitcnt lgkmcnt(2)
	v_max_f32_e32 v5, v5, v5
	ds_bpermute_b32 v10, v15, v1
	s_waitcnt lgkmcnt(2)
	v_max_f32_e32 v4, v4, v4
	v_max_f32_e32 v2, v2, v5
	v_max_f32_e32 v4, v6, v4
	ds_bpermute_b32 v5, v15, v2
	ds_bpermute_b32 v6, v14, v4
	s_waitcnt lgkmcnt(3)
	v_max_f32_e32 v9, v9, v9
	s_waitcnt lgkmcnt(2)
	v_max_f32_e32 v10, v10, v10
	v_max_f32_e32 v0, v0, v9
	v_max_f32_e32 v1, v1, v10
	ds_bpermute_b32 v9, v16, v0
	s_waitcnt lgkmcnt(2)
	v_max_f32_e32 v5, v5, v5
	ds_bpermute_b32 v10, v16, v1
	s_waitcnt lgkmcnt(2)
	v_max_f32_e32 v6, v6, v6
	v_max_f32_e32 v2, v2, v5
	v_max_f32_e32 v4, v4, v6
	ds_bpermute_b32 v5, v16, v2
	ds_bpermute_b32 v6, v15, v4
	ds_bpermute_b32 v12, v14, v8
	s_waitcnt lgkmcnt(4)
	v_max_f32_e32 v9, v9, v9
	s_waitcnt lgkmcnt(3)
	v_max_f32_e32 v10, v10, v10
	v_max_f32_e32 v0, v0, v9
	v_max_f32_e32 v1, v1, v10
	ds_bpermute_b32 v9, v17, v0
	s_waitcnt lgkmcnt(3)
	v_max_f32_e32 v5, v5, v5
	ds_bpermute_b32 v10, v17, v1
	s_waitcnt lgkmcnt(3)
	v_max_f32_e32 v6, v6, v6
	v_max_f32_e32 v2, v2, v5
	s_waitcnt lgkmcnt(2)
	v_add_f32_e32 v8, v8, v12
	v_max_f32_e32 v4, v4, v6
	ds_bpermute_b32 v5, v17, v2
	ds_bpermute_b32 v11, v15, v7
	ds_bpermute_b32 v6, v16, v4
	ds_bpermute_b32 v12, v15, v8
	s_waitcnt lgkmcnt(5)
	v_max_f32_e32 v9, v9, v9
	s_waitcnt lgkmcnt(4)
	v_max_f32_e32 v10, v10, v10
	v_max_f32_e32 v0, v0, v9
	v_max_f32_e32 v1, v1, v10
	v_mul_f32_e32 v0, 0xc138a3c4, v0
	s_waitcnt lgkmcnt(3)
	v_max_f32_e32 v5, v5, v5
	v_mul_f32_e32 v0, v0, v1
	s_waitcnt lgkmcnt(1)
	v_max_f32_e32 v6, v6, v6
	v_max_f32_e32 v2, v2, v5
	v_readfirstlane_b32 s4, v0
	v_add_f32_e32 v1, v7, v11
	s_waitcnt lgkmcnt(0)
	v_add_f32_e32 v5, v8, v12
	v_mul_f32_e32 v0, s4, v3
	ds_bpermute_b32 v3, v16, v1
	v_max_f32_e32 v4, v4, v6
	ds_bpermute_b32 v6, v16, v5
	ds_bpermute_b32 v7, v17, v4
	v_mul_f32_e32 v2, 0xc1028f5c, v2
	s_waitcnt lgkmcnt(2)
	v_add_f32_e32 v1, v1, v3
	ds_bpermute_b32 v3, v17, v1
	s_waitcnt lgkmcnt(2)
	v_add_f32_e32 v5, v5, v6
	ds_bpermute_b32 v6, v17, v5
	s_waitcnt lgkmcnt(2)
	v_max_f32_e32 v7, v7, v7
	v_max_f32_e32 v4, v4, v7
	s_waitcnt lgkmcnt(1)
	v_add_f32_e32 v1, v1, v3
	v_mul_f32_e32 v1, 0x3fb8aa3b, v1
	s_waitcnt lgkmcnt(0)
	v_add_f32_e32 v3, v5, v6
	v_mul_f32_e32 v3, 0x3fb8aa3b, v3
	v_exp_f32_e32 v1, v1
	v_exp_f32_e32 v3, v3
	v_mul_f32_e32 v2, v2, v4
	v_sub_f32_e32 v1, v1, v3
	v_readfirstlane_b32 s4, v2
	v_readfirstlane_b32 s29, v1
	s_nop 3
	v_writelane_b32 v255, s4, 20
	v_writelane_b32 v255, s29, 21
	v_writelane_b32 v255, s8, 22
	v_writelane_b32 v255, s9, 23
	v_mov_b32_e32 v1, 0
	s_cbranch_scc1 .LBB0_597
	v_mbcnt_lo_u32_b32 v1, -1, v1
	s_cmpk_eq_i32 s24, 0x100
	v_mbcnt_hi_u32_b32 v1, -1, v1
	s_cselect_b64 s[14:15], -1, 0
	s_lshl_b32 s5, s2, 1
	s_and_b32 s5, s5, 14
	s_ashr_i32 s10, s2, 7
	v_and_b32_e32 v3, 15, v1
	v_ashrrev_i32_e32 v215, 4, v1
	s_movk_i32 s12, 0x140
	s_add_i32 s5, s5, s10
	s_add_i32 s10, s63, 0
	v_ashrrev_i32_e32 v2, 5, v1
	v_lshlrev_b32_e32 v16, 3, v3
	v_lshlrev_b32_e32 v17, 4, v3
	v_mul_lo_u32 v3, v215, s12
	v_and_b32_e32 v214, 31, v1
	v_bfe_u32 v4, v1, 2, 2
	v_add_u32_e32 v18, s10, v3
	v_lshlrev_b32_e32 v20, 2, v2
	v_and_b32_e32 v3, 16, v1
	v_lshlrev_b32_e32 v1, 2, v1
	v_lshlrev_b32_e32 v210, 3, v2
	s_movk_i32 s11, 0x110
	v_lshlrev_b32_e32 v19, 4, v2
	v_or_b32_e32 v2, v20, v4
	v_and_or_b32 v1, v1, 12, v3
	v_mul_lo_u32 v5, v215, s11
	v_mul_lo_u32 v2, v2, s12
	v_lshlrev_b32_e32 v21, 1, v1
	v_mov_b32_e32 v1, s10
	v_add_u32_e32 v22, s10, v5
	v_mad_u32_u24 v23, v214, s11, v1
	v_add_u32_e32 v24, s10, v2
	s_ashr_i32 s28, s5, 3
	s_mov_b32 s37, 0
	v_ashrrev_i32_e32 v211, 31, v210
	v_mov_b32_e32 v1, v0
	v_mov_b32_e32 v2, v0
	v_mov_b32_e32 v3, v0
	v_mov_b32_e32 v4, v0
	v_mov_b32_e32 v5, v0
	v_mov_b32_e32 v6, v0
	v_mov_b32_e32 v7, v0
	v_mov_b32_e32 v8, v0
	v_mov_b32_e32 v9, v0
	v_mov_b32_e32 v10, v0
	v_mov_b32_e32 v11, v0
	v_mov_b32_e32 v12, v0
	v_mov_b32_e32 v13, v0
	v_mov_b32_e32 v14, v0
	v_mov_b32_e32 v15, v0
	v_add_u32_e32 v216, 64, v20
	s_movk_i32 s44, 0x3000
	v_lshlrev_b32_e32 v208, 1, v16
	s_mov_b64 s[38:39], 0x800
	s_movk_i32 s45, 0x81
	v_add_u32_e32 v217, v24, v21
	v_mov_b32_e32 v218, 0x3000
	v_add_u32_e32 v219, v22, v17
	v_add_u32_e32 v220, v18, v17
	v_add_u32_e32 v221, v23, v19
	s_mov_b32 s46, s60
	s_branch .LBB0_582

.Lxo_hdr2:
	v_readlane_b32 s4, v255, 20
	v_readlane_b32 s29, v255, 21
	v_readlane_b32 s8, v255, 22
	v_readlane_b32 s9, v255, 23
	s_bfe_u32 s61, s97, 0x20006
	s_lshl_b32 s57, s61, 5
	s_nop 3
	s_add_u32 s14, s26, 0x13200000
	s_addc_u32 s15, s27, 0
	s_cmpk_eq_i32 s24, 0x100
	s_waitcnt vmcnt(21)
	v_mov_b32_e32 v179, 0
	s_waitcnt lgkmcnt(0)
	v_mov_b32_e32 v1, 0
	s_cselect_b64 s[36:37], -1, 0
	s_cmpk_gt_i32 s2, 0x1ff
	s_barrier
	v_mov_b32_e32 v2, 0x3fb8aa3b
	v_mbcnt_lo_u32_b32 v1, -1, v1
	v_mul_f32_e32 v2, s4, v2
	v_mbcnt_hi_u32_b32 v19, -1, v1
	v_readlane_b32 s4, v255, 0
	s_waitcnt vmcnt(20)
	v_and_b32_e32 v180, 31, v19
	v_bfe_u32 v21, v19, 5, 1
	v_add_u32_e32 v1, s4, v19
	v_and_b32_e32 v22, 16, v19
	v_ashrrev_i32_e32 v182, 4, v1
	v_and_b32_e32 v1, 15, v19
	s_movk_i32 s12, 0x140
	v_bfe_u32 v23, v19, 2, 2
	v_lshlrev_b32_e32 v19, 2, v19
	v_lshlrev_b32_e32 v18, 3, v21
	v_lshlrev_b32_e32 v20, 3, v1
	v_lshlrev_b32_e32 v24, 4, v1
	v_mul_lo_u32 v1, v182, s12
	v_lshl_or_b32 v21, v21, 2, v23
	v_and_or_b32 v19, v19, 12, v22
	s_waitcnt vmcnt(17)
	v_add3_u32 v184, 0, v1, v24
	s_movk_i32 s12, 0xffd0
	v_mul_u32_u24_e32 v21, 0x140, v21
	v_lshlrev_b32_e32 v19, 1, v19
	s_load_dwordx2 s[10:11], s[0:1], 0x78
	v_mad_u64_u32 v[186:187], s[38:39], v182, s12, v[184:185]
	v_add3_u32 v185, 0, v21, v19
	v_mov_b32_e32 v19, 0x3e4ccccd
	v_add_f32_e32 v224, s29, v19
	s_movk_i32 s29, 0x3000
	v_or_b32_e32 v26, s94, v18
	v_mad_i64_i32 v[22:23], s[38:39], v182, s29, 0
	s_mov_b32 s13, 0
	v_mul_u32_u24_e32 v25, 0x110, v180
	v_lshlrev_b32_e32 v26, 1, v26
	s_lshl_b32 s12, s61, 14
	v_or_b32_e32 v22, v22, v24
	s_and_b32 s4, s2, 7
	s_ashr_i32 s5, s2, 3
	v_ashrrev_i32_e32 v183, 31, v182
	v_add_u32_e32 v1, 0x8800, v184
	v_mov_b32_e32 v3, v2
	v_mov_b32_e32 v4, v2
	v_mov_b32_e32 v5, v2
	v_mov_b32_e32 v6, v2
	v_mov_b32_e32 v7, v2
	v_mov_b32_e32 v8, v2
	v_mov_b32_e32 v9, v2
	v_mov_b32_e32 v10, v2
	v_mov_b32_e32 v11, v2
	v_mov_b32_e32 v12, v2
	v_mov_b32_e32 v13, v2
	v_mov_b32_e32 v14, v2
	v_mov_b32_e32 v15, v2
	v_mov_b32_e32 v16, v2
	v_mov_b32_e32 v17, v2
	v_add3_u32 v181, 0, v25, v26
	v_add_u32_e32 v238, 0x21480, v185
	v_add_u32_e32 v239, 0x21e80, v185
	v_add_u32_e32 v240, 0x214c0, v185
	v_add_u32_e32 v241, 0x21ec0, v185
	v_add_u32_e32 v242, 0x22800, v185
	v_add_u32_e32 v243, 0x23200, v185
	v_add_u32_e32 v244, 0x22840, v185
	v_add_u32_e32 v245, 0x23240, v185
	v_add_u32_e32 v246, 0x22880, v185
	v_add_u32_e32 v247, 0x23280, v185
	v_add_u32_e32 v248, 0x228c0, v185
	v_add_u32_e32 v249, 0x232c0, v185
	v_add_u32_e32 v250, 0x23c00, v185
	v_add_u32_e32 v251, 0x24600, v185
	v_add_u32_e32 v252, 0x23c40, v185
	v_add_u32_e32 v253, 0x24640, v185
	v_add_u32_e32 v254, 0x23c80, v185
	v_add_u32_e32 v187, 0x24680, v185
	v_add_u32_e32 v222, 0x23cc0, v185
	v_add_u32_e32 v223, 0x246c0, v185
	s_add_i32 s28, s12, 0
	s_waitcnt vmcnt(16)
	v_lshl_add_u64 v[188:189], s[26:27], 0, v[22:23]
	s_lshl_b32 s38, s94, 1
	s_mov_b32 s39, s13
	v_lshlrev_b32_e32 v178, 1, v18
	s_mov_b64 s[40:41], 0x1800
	s_movk_i32 s48, 0x1000
	v_lshlrev_b32_e32 v190, 1, v20
	s_mov_b64 s[42:43], 0x2000
	s_movk_i32 s49, 0x2000
	s_mov_b32 s50, 0x62000
	s_mov_b32 s51, 0xc2000
	s_mov_b32 s56, 0x122000
	s_mov_b32 s58, 0xd182000
	s_mov_b32 s59, 0xd1e2000
	s_mov_b32 s61, 0xd242000
	s_mov_b32 s68, 0xd2a2000
	v_mov_b32_e32 v225, 0x3000
	s_add_i32 s69, s2, s24
	s_branch .LBB0_654
.LBB0_653:
	s_add_i32 s69, s69, s24
	s_cmpk_gt_i32 s69, 0x1ff
	s_barrier
	s_cbranch_scc1 .Lxo_done
	s_cmpk_eq_i32 s24, 0x100
	s_cbranch_scc0 .LBB0_654
	s_cmpk_lt_u32 s2, 0x80
	s_cbranch_scc1 .LBB0_654
	s_branch .LBB0_660
.Lxo_done:
	s_cmpk_eq_i32 s24, 0x100
	s_cbranch_scc0 .LBB0_660
	s_cmpk_lt_u32 s2, 0x80
	s_cbranch_scc1 .LBB0_660
	s_branch .LBB0_677

.LBB0_677:
	s_cmpk_gt_i32 s69, 0x1ff
	s_cbranch_scc1 .Lxo_cont
	s_cmpk_eq_i32 s24, 0x100
	s_cbranch_scc0 .Lxo_cont
	s_cmpk_lt_u32 s2, 0x80
	s_cbranch_scc0 .Lxo_hdr2
